# grid barrier: non-leader workgroups poll the cross-XCD generation word directly (one relay hop less) (run 1)
# speedup vs baseline: 1.0125x; 1.0036x over previous
.LBB0_98:
	s_or_b64 exec, exec, s[10:11]
	v_cvt_f32_u32_e32 v4, v2
	s_waitcnt vmcnt(0)
	v_readfirstlane_b32 s3, v3
	v_sub_u32_e32 v3, 0, v2
	v_rcp_iflag_f32_e32 v4, v4
	v_add_u32_e32 v5, s3, v1
	v_mul_f32_e32 v4, 0x4f7ffffe, v4
	v_cvt_u32_f32_e32 v4, v4
	v_mul_lo_u32 v1, v3, v4
	v_mul_hi_u32 v1, v4, v1
	v_add_u32_e32 v1, v4, v1
	v_mul_hi_u32 v1, v5, v1
	v_mul_lo_u32 v3, v1, v2
	v_sub_u32_e32 v3, v5, v3
	v_add_u32_e32 v4, 1, v1
	v_cmp_ge_u32_e32 vcc, v3, v2
	s_nop 1
	v_cndmask_b32_e32 v1, v1, v4, vcc
	v_sub_u32_e32 v4, v3, v2
	v_cndmask_b32_e32 v3, v3, v4, vcc
	v_add_u32_e32 v4, 1, v1
	v_cmp_ge_u32_e32 vcc, v3, v2
	v_add_u32_e32 v3, 1, v5
	s_nop 0
	v_cndmask_b32_e32 v1, v1, v4, vcc
	v_mul_lo_u32 v4, v2, v1
	v_add_u32_e32 v2, v4, v2
	v_cmp_ne_u32_e32 vcc, v3, v2
	s_and_saveexec_b64 s[8:9], vcc
	s_xor_b64 s[8:9], exec, s[8:9]
	s_cbranch_execz .LBB0_112
	s_waitcnt lgkmcnt(0)
	v_mov_b32_e32 v0, 0x3500
	global_load_dword v0, v0, s[78:79] sc1
	s_add_u32 s12, s78, 0x3500
	s_addc_u32 s13, s79, 0
	s_waitcnt vmcnt(0)
	v_cmp_eq_u32_e32 vcc, v0, v1
	s_and_saveexec_b64 s[10:11], vcc
	s_cbranch_execz .LBB0_111
	s_mov_b32 s3, 1
	s_mov_b64 s[14:15], 0
	v_mov_b32_e32 v0, 0
	s_branch .LBB0_102

.LBB0_171:
	s_or_b64 exec, exec, s[8:9]
	v_cvt_f32_u32_e32 v4, v2
	s_waitcnt vmcnt(0)
	v_readfirstlane_b32 s6, v3
	v_sub_u32_e32 v3, 0, v2
	v_rcp_iflag_f32_e32 v4, v4
	v_add_u32_e32 v5, s6, v1
	v_mul_f32_e32 v4, 0x4f7ffffe, v4
	v_cvt_u32_f32_e32 v4, v4
	v_mul_lo_u32 v1, v3, v4
	v_mul_hi_u32 v1, v4, v1
	v_add_u32_e32 v1, v4, v1
	v_mul_hi_u32 v1, v5, v1
	v_mul_lo_u32 v3, v1, v2
	v_sub_u32_e32 v3, v5, v3
	v_add_u32_e32 v4, 1, v1
	v_cmp_ge_u32_e32 vcc, v3, v2
	s_nop 1
	v_cndmask_b32_e32 v1, v1, v4, vcc
	v_sub_u32_e32 v4, v3, v2
	v_cndmask_b32_e32 v3, v3, v4, vcc
	v_add_u32_e32 v4, 1, v1
	v_cmp_ge_u32_e32 vcc, v3, v2
	v_add_u32_e32 v3, 1, v5
	s_nop 0
	v_cndmask_b32_e32 v1, v1, v4, vcc
	v_mul_lo_u32 v4, v2, v1
	v_add_u32_e32 v2, v4, v2
	v_cmp_ne_u32_e32 vcc, v3, v2
	s_and_saveexec_b64 s[6:7], vcc
	s_xor_b64 s[6:7], exec, s[6:7]
	s_cbranch_execz .LBB0_185
	s_waitcnt lgkmcnt(0)
	v_mov_b32_e32 v0, 0x3500
	global_load_dword v0, v0, s[78:79] sc1
	s_add_u32 s10, s78, 0x3500
	s_addc_u32 s11, s79, 0
	s_waitcnt vmcnt(0)
	v_cmp_eq_u32_e32 vcc, v0, v1
	s_and_saveexec_b64 s[8:9], vcc
	s_cbranch_execz .LBB0_184
	s_mov_b32 s22, 1
	s_mov_b64 s[12:13], 0
	v_mov_b32_e32 v0, 0
	s_branch .LBB0_175

.LBB0_1286:
	s_or_b64 exec, exec, s[10:11]
	v_cvt_f32_u32_e32 v4, v2
	s_waitcnt vmcnt(0)
	v_readfirstlane_b32 s8, v3
	v_sub_u32_e32 v3, 0, v2
	v_rcp_iflag_f32_e32 v4, v4
	v_add_u32_e32 v5, s8, v1
	v_mul_f32_e32 v4, 0x4f7ffffe, v4
	v_cvt_u32_f32_e32 v4, v4
	v_mul_lo_u32 v1, v3, v4
	v_mul_hi_u32 v1, v4, v1
	v_add_u32_e32 v1, v4, v1
	v_mul_hi_u32 v1, v5, v1
	v_mul_lo_u32 v3, v1, v2
	v_sub_u32_e32 v3, v5, v3
	v_add_u32_e32 v4, 1, v1
	v_cmp_ge_u32_e32 vcc, v3, v2
	s_nop 1
	v_cndmask_b32_e32 v1, v1, v4, vcc
	v_sub_u32_e32 v4, v3, v2
	v_cndmask_b32_e32 v3, v3, v4, vcc
	v_add_u32_e32 v4, 1, v1
	v_cmp_ge_u32_e32 vcc, v3, v2
	v_add_u32_e32 v3, 1, v5
	s_nop 0
	v_cndmask_b32_e32 v1, v1, v4, vcc
	v_mul_lo_u32 v4, v2, v1
	v_add_u32_e32 v2, v4, v2
	v_cmp_ne_u32_e32 vcc, v3, v2
	s_and_saveexec_b64 s[8:9], vcc
	s_xor_b64 s[8:9], exec, s[8:9]
	s_cbranch_execz .LBB0_1300
	s_waitcnt lgkmcnt(0)
	v_mov_b32_e32 v0, 0x3500
	global_load_dword v0, v0, s[78:79] sc1
	s_add_u32 s12, s78, 0x3500
	s_addc_u32 s13, s79, 0
	s_waitcnt vmcnt(0)
	v_cmp_eq_u32_e32 vcc, v0, v1
	s_and_saveexec_b64 s[10:11], vcc
	s_cbranch_execz .LBB0_1299
	s_mov_b32 s24, 1
	s_mov_b64 s[14:15], 0
	v_mov_b32_e32 v0, 0
	s_branch .LBB0_1290

.LBB0_2705:
	s_or_b64 exec, exec, s[10:11]
	v_cvt_f32_u32_e32 v4, v2
	s_waitcnt vmcnt(0)
	v_readfirstlane_b32 s6, v3
	v_sub_u32_e32 v3, 0, v2
	v_rcp_iflag_f32_e32 v4, v4
	v_add_u32_e32 v5, s6, v1
	v_mul_f32_e32 v4, 0x4f7ffffe, v4
	v_cvt_u32_f32_e32 v4, v4
	v_mul_lo_u32 v1, v3, v4
	v_mul_hi_u32 v1, v4, v1
	v_add_u32_e32 v1, v4, v1
	v_mul_hi_u32 v1, v5, v1
	v_mul_lo_u32 v3, v1, v2
	v_sub_u32_e32 v3, v5, v3
	v_add_u32_e32 v4, 1, v1
	v_cmp_ge_u32_e32 vcc, v3, v2
	s_nop 1
	v_cndmask_b32_e32 v1, v1, v4, vcc
	v_sub_u32_e32 v4, v3, v2
	v_cndmask_b32_e32 v3, v3, v4, vcc
	v_add_u32_e32 v4, 1, v1
	v_cmp_ge_u32_e32 vcc, v3, v2
	v_add_u32_e32 v3, 1, v5
	s_nop 0
	v_cndmask_b32_e32 v1, v1, v4, vcc
	v_mul_lo_u32 v4, v2, v1
	v_add_u32_e32 v2, v4, v2
	v_cmp_ne_u32_e32 vcc, v3, v2
	s_and_saveexec_b64 s[6:7], vcc
	s_xor_b64 s[6:7], exec, s[6:7]
	s_cbranch_execz .LBB0_2719
	s_waitcnt lgkmcnt(0)
	v_mov_b32_e32 v0, 0x3500
	global_load_dword v0, v0, s[78:79] sc1
	s_add_u32 s12, s78, 0x3500
	s_addc_u32 s13, s79, 0
	s_waitcnt vmcnt(0)
	v_cmp_eq_u32_e32 vcc, v0, v1
	s_and_saveexec_b64 s[10:11], vcc
	s_cbranch_execz .LBB0_2718
	s_mov_b32 s24, 1
	s_mov_b64 s[14:15], 0
	v_mov_b32_e32 v0, 0
	s_branch .LBB0_2709

.LBB0_2814:
	s_or_b64 exec, exec, s[6:7]
	v_cvt_f32_u32_e32 v4, v2
	s_waitcnt vmcnt(0)
	v_readfirstlane_b32 s4, v3
	v_sub_u32_e32 v3, 0, v2
	v_rcp_iflag_f32_e32 v4, v4
	v_add_u32_e32 v5, s4, v1
	v_mul_f32_e32 v4, 0x4f7ffffe, v4
	v_cvt_u32_f32_e32 v4, v4
	v_mul_lo_u32 v1, v3, v4
	v_mul_hi_u32 v1, v4, v1
	v_add_u32_e32 v1, v4, v1
	v_mul_hi_u32 v1, v5, v1
	v_mul_lo_u32 v3, v1, v2
	v_sub_u32_e32 v3, v5, v3
	v_add_u32_e32 v4, 1, v1
	v_cmp_ge_u32_e32 vcc, v3, v2
	s_nop 1
	v_cndmask_b32_e32 v1, v1, v4, vcc
	v_sub_u32_e32 v4, v3, v2
	v_cndmask_b32_e32 v3, v3, v4, vcc
	v_add_u32_e32 v4, 1, v1
	v_cmp_ge_u32_e32 vcc, v3, v2
	v_add_u32_e32 v3, 1, v5
	s_nop 0
	v_cndmask_b32_e32 v1, v1, v4, vcc
	v_mul_lo_u32 v4, v2, v1
	v_add_u32_e32 v2, v4, v2
	v_cmp_ne_u32_e32 vcc, v3, v2
	s_and_saveexec_b64 s[4:5], vcc
	s_xor_b64 s[4:5], exec, s[4:5]
	s_cbranch_execz .LBB0_2828
	s_waitcnt lgkmcnt(0)
	v_mov_b32_e32 v0, 0x3500
	global_load_dword v0, v0, s[78:79] sc1
	s_add_u32 s8, s78, 0x3500
	s_addc_u32 s9, s79, 0
	s_waitcnt vmcnt(0)
	v_cmp_eq_u32_e32 vcc, v0, v1
	s_and_saveexec_b64 s[6:7], vcc
	s_cbranch_execz .LBB0_2827
	s_mov_b32 s20, 1
	s_mov_b64 s[10:11], 0
	v_mov_b32_e32 v0, 0
	s_branch .LBB0_2818
